# barriers after the mixing phases: the first workgroup of each XCD to arrive starts a background L2 write-back, so the last arriver's write-back has less to flush
# speedup vs baseline: 1.0065x; 1.0065x over previous
; __device__ __forceinline__ void fast_grid_barrier(unsigned* base, int seam, int tid) {
;     asm volatile("s_waitcnt vmcnt(0)" ::: "memory");
;     __syncthreads();
;     if (tid == 0) {
;         unsigned* cnt = base + seam * 128;
;         unsigned* flg = cnt + 64;
;         __builtin_amdgcn_fence(__ATOMIC_RELEASE, "agent");
;         asm volatile("s_waitcnt vmcnt(0)" ::: "memory");
;         const unsigned old = __hip_atomic_fetch_add(cnt, 1u, __ATOMIC_RELAXED, __HIP_MEMORY_SCOPE_AGENT);
;         if (old == gridDim.x - 1) __hip_atomic_store(flg, 1u, __ATOMIC_RELAXED, __HIP_MEMORY_SCOPE_AGENT);
;         else { unsigned sp = 0; while (__hip_atomic_load(flg, __ATOMIC_RELAXED, __HIP_MEMORY_SCOPE_AGENT) == 0u) { __builtin_amdgcn_s_sleep(2); if (++sp > (1u << 22)) break; } }
;         __builtin_amdgcn_fence(__ATOMIC_ACQUIRE, "agent");
;         asm volatile("s_waitcnt vmcnt(0)" ::: "memory");
;     }
;     __syncthreads();
; }
.LBB0_84:
	s_cmp_lt_i32 s47, 3
	s_cbranch_scc1 .LBB0_101
	s_waitcnt vmcnt(0)
	v_cmp_eq_u32_e32 vcc, 0, v202
	s_barrier
	s_and_saveexec_b64 s[0:1], vcc
	s_cbranch_execz .LBB0_100
	s_load_dwordx2 s[4:5], s[84:85], 0x90
	s_lshl_b32 s3, s98, 6
	v_mov_b32_e32 v0, s3
	v_mov_b32_e32 v2, 1
	s_waitcnt lgkmcnt(0)
	s_add_u32 s4, s4, 0x1400
	s_addc_u32 s5, s5, 0
	s_lshl_b32 s6, s98, 2
	v_mov_b32_e32 v1, s6
	v_mov_b32_e32 v2, 0
	global_load_dword v1, v1, s[4:5] sc1
	global_load_dword v2, v2, s[4:5] offset:64 sc1
	s_waitcnt vmcnt(0)
	v_readfirstlane_b32 s99, v1
	v_readfirstlane_b32 s100, v2
	v_mov_b32_e32 v2, 1
	s_nop 3
	global_atomic_add v1, v0, v2, s[4:5] offset:128 sc0
	s_mul_i32 s6, s99, 1
	s_add_i32 s3, s6, -1
	s_lshl_b32 s6, s98, 6
	s_sub_u32 s6, s4, s6
	s_subb_u32 s7, s5, 0
	s_mul_i32 s4, s100, 1
	s_waitcnt vmcnt(0)
	v_cmp_ne_u32_e32 vcc, s3, v1
	s_cbranch_vccnz .Lsm1_early
	buffer_wbl2 sc1
	s_waitcnt vmcnt(0)
	global_atomic_add v0, v2, s[6:7] offset:2176
	s_branch .Lsm1_wtop
.Lsm1_early:
.Lsm1_wtop:
	s_mov_b32 s3, 0x8000

; __device__ __forceinline__ void fast_grid_barrier(unsigned* base, int seam, int tid) {
;     asm volatile("s_waitcnt vmcnt(0)" ::: "memory");
;     __syncthreads();
;     if (tid == 0) {
;         unsigned* cnt = base + seam * 128;
;         unsigned* flg = cnt + 64;
;         __builtin_amdgcn_fence(__ATOMIC_RELEASE, "agent");
;         asm volatile("s_waitcnt vmcnt(0)" ::: "memory");
;         const unsigned old = __hip_atomic_fetch_add(cnt, 1u, __ATOMIC_RELAXED, __HIP_MEMORY_SCOPE_AGENT);
;         if (old == gridDim.x - 1) __hip_atomic_store(flg, 1u, __ATOMIC_RELAXED, __HIP_MEMORY_SCOPE_AGENT);
;         else { unsigned sp = 0; while (__hip_atomic_load(flg, __ATOMIC_RELAXED, __HIP_MEMORY_SCOPE_AGENT) == 0u) { __builtin_amdgcn_s_sleep(2); if (++sp > (1u << 22)) break; } }
;         __builtin_amdgcn_fence(__ATOMIC_ACQUIRE, "agent");
;         asm volatile("s_waitcnt vmcnt(0)" ::: "memory");
;     }
;     __syncthreads();
; }
.LBB0_167:
	s_waitcnt vmcnt(0)
	v_cmp_eq_u32_e32 vcc, 0, v202
	s_waitcnt vmcnt(0) lgkmcnt(0)
	s_barrier
	s_and_saveexec_b64 s[0:1], vcc
	s_cbranch_execz .LBB0_182
	s_load_dwordx2 s[4:5], s[84:85], 0x90
	s_lshl_b32 s3, s98, 6
	v_mov_b32_e32 v0, s3
	v_mov_b32_e32 v2, 1
	s_waitcnt lgkmcnt(0)
	s_add_u32 s4, s4, 0x1400
	s_addc_u32 s5, s5, 0
	global_atomic_add v1, v0, v2, s[4:5] offset:128 sc0
	s_mul_i32 s6, s99, 2
	s_add_i32 s3, s6, -1
	s_lshl_b32 s6, s98, 6
	s_sub_u32 s6, s4, s6
	s_subb_u32 s7, s5, 0
	s_mul_i32 s4, s100, 2
	s_waitcnt vmcnt(0)
	v_cmp_ne_u32_e32 vcc, s3, v1
	s_cbranch_vccnz .Lsm2_early
	buffer_wbl2 sc1
	s_waitcnt vmcnt(0)
	global_atomic_add v0, v2, s[6:7] offset:2176
	s_branch .Lsm2_wtop

; __device__ __forceinline__ void fast_grid_barrier(unsigned* base, int seam, int tid) {
;     asm volatile("s_waitcnt vmcnt(0)" ::: "memory");
;     __syncthreads();
;     if (tid == 0) {
;         unsigned* cnt = base + seam * 128;
;         unsigned* flg = cnt + 64;
;         __builtin_amdgcn_fence(__ATOMIC_RELEASE, "agent");
;         asm volatile("s_waitcnt vmcnt(0)" ::: "memory");
;         const unsigned old = __hip_atomic_fetch_add(cnt, 1u, __ATOMIC_RELAXED, __HIP_MEMORY_SCOPE_AGENT);
;         if (old == gridDim.x - 1) __hip_atomic_store(flg, 1u, __ATOMIC_RELAXED, __HIP_MEMORY_SCOPE_AGENT);
;         else { unsigned sp = 0; while (__hip_atomic_load(flg, __ATOMIC_RELAXED, __HIP_MEMORY_SCOPE_AGENT) == 0u) { __builtin_amdgcn_s_sleep(2); if (++sp > (1u << 22)) break; } }
;         __builtin_amdgcn_fence(__ATOMIC_ACQUIRE, "agent");
;         asm volatile("s_waitcnt vmcnt(0)" ::: "memory");
;     }
;     __syncthreads();
; }
.LBB0_544:
	s_waitcnt lgkmcnt(0)
	s_cmp_lt_i32 s47, 5
	s_cbranch_scc1 .LBB0_561
	s_waitcnt vmcnt(0)
	s_waitcnt vmcnt(0)
	s_barrier
	s_mov_b64 s[0:1], exec
	v_readlane_b32 s4, v249, 28
	v_readlane_b32 s5, v249, 29
	s_and_b64 s[4:5], s[0:1], s[4:5]
	s_mov_b64 exec, s[4:5]
	s_cbranch_execz .LBB0_560
	s_load_dwordx2 s[4:5], s[84:85], 0x90
	s_lshl_b32 s3, s98, 6
	v_mov_b32_e32 v0, s3
	v_mov_b32_e32 v2, 1
	s_waitcnt lgkmcnt(0)
	s_add_u32 s4, s4, 0x1400
	s_addc_u32 s5, s5, 0
	global_atomic_add v1, v0, v2, s[4:5] offset:128 sc0
	s_mul_i32 s6, s99, 3
	s_add_i32 s3, s6, -1
	s_lshl_b32 s6, s98, 6
	s_sub_u32 s6, s4, s6
	s_subb_u32 s7, s5, 0
	s_mul_i32 s4, s100, 3
	s_waitcnt vmcnt(0)
	v_cmp_ne_u32_e32 vcc, s3, v1
	s_cbranch_vccnz .Lsm3_early
	buffer_wbl2 sc1
	s_waitcnt vmcnt(0)
	global_atomic_add v0, v2, s[6:7] offset:2176
	s_branch .Lsm3_wtop
.Lsm3_early:
	s_mul_i32 s3, s99, 2
	v_cmp_ne_u32_e32 vcc, s3, v1
	s_cbranch_vccnz .Lsm3_wtop
	buffer_wbl2 sc1

; __device__ __forceinline__ void fast_grid_barrier(unsigned* base, int seam, int tid) {
;     asm volatile("s_waitcnt vmcnt(0)" ::: "memory");
;     __syncthreads();
;     if (tid == 0) {
;         unsigned* cnt = base + seam * 128;
;         unsigned* flg = cnt + 64;
;         __builtin_amdgcn_fence(__ATOMIC_RELEASE, "agent");
;         asm volatile("s_waitcnt vmcnt(0)" ::: "memory");
;         const unsigned old = __hip_atomic_fetch_add(cnt, 1u, __ATOMIC_RELAXED, __HIP_MEMORY_SCOPE_AGENT);
;         if (old == gridDim.x - 1) __hip_atomic_store(flg, 1u, __ATOMIC_RELAXED, __HIP_MEMORY_SCOPE_AGENT);
;         else { unsigned sp = 0; while (__hip_atomic_load(flg, __ATOMIC_RELAXED, __HIP_MEMORY_SCOPE_AGENT) == 0u) { __builtin_amdgcn_s_sleep(2); if (++sp > (1u << 22)) break; } }
;         __builtin_amdgcn_fence(__ATOMIC_ACQUIRE, "agent");
;         asm volatile("s_waitcnt vmcnt(0)" ::: "memory");
;     }
;     __syncthreads();
; }
.LBB0_586:
	s_waitcnt lgkmcnt(0)
	s_cmp_lt_i32 s47, 6
	s_cbranch_scc1 .LBB0_603
	s_waitcnt vmcnt(0)
	v_cmp_eq_u32_e32 vcc, 0, v202
	s_barrier
	s_and_saveexec_b64 s[0:1], vcc
	s_cbranch_execz .LBB0_602
	s_load_dwordx2 s[4:5], s[84:85], 0x90
	s_lshl_b32 s3, s98, 6
	v_mov_b32_e32 v0, s3
	v_mov_b32_e32 v2, 1
	s_waitcnt lgkmcnt(0)
	s_add_u32 s4, s4, 0x1400
	s_addc_u32 s5, s5, 0
	global_atomic_add v1, v0, v2, s[4:5] offset:128 sc0
	s_mul_i32 s6, s99, 4
	s_add_i32 s3, s6, -1
	s_lshl_b32 s6, s98, 6
	s_sub_u32 s6, s4, s6
	s_subb_u32 s7, s5, 0
	s_mul_i32 s4, s100, 4
	s_waitcnt vmcnt(0)
	v_cmp_ne_u32_e32 vcc, s3, v1
	s_cbranch_vccnz .Lsm4_early
	global_atomic_add v0, v2, s[6:7] offset:2176
	s_branch .Lsm4_wtop

; __device__ __forceinline__ void fast_grid_barrier(unsigned* base, int seam, int tid) {
;     asm volatile("s_waitcnt vmcnt(0)" ::: "memory");
;     __syncthreads();
;     if (tid == 0) {
;         unsigned* cnt = base + seam * 128;
;         unsigned* flg = cnt + 64;
;         __builtin_amdgcn_fence(__ATOMIC_RELEASE, "agent");
;         asm volatile("s_waitcnt vmcnt(0)" ::: "memory");
;         const unsigned old = __hip_atomic_fetch_add(cnt, 1u, __ATOMIC_RELAXED, __HIP_MEMORY_SCOPE_AGENT);
;         if (old == gridDim.x - 1) __hip_atomic_store(flg, 1u, __ATOMIC_RELAXED, __HIP_MEMORY_SCOPE_AGENT);
;         else { unsigned sp = 0; while (__hip_atomic_load(flg, __ATOMIC_RELAXED, __HIP_MEMORY_SCOPE_AGENT) == 0u) { __builtin_amdgcn_s_sleep(2); if (++sp > (1u << 22)) break; } }
;         __builtin_amdgcn_fence(__ATOMIC_ACQUIRE, "agent");
;         asm volatile("s_waitcnt vmcnt(0)" ::: "memory");
;     }
;     __syncthreads();
; }
.LBB0_609:
	s_cmp_lt_i32 s47, 7
	s_cbranch_scc1 .LBB0_626
	s_waitcnt vmcnt(0)
	v_cmp_eq_u32_e32 vcc, 0, v202
	s_waitcnt vmcnt(0) lgkmcnt(0)
	s_barrier
	s_and_saveexec_b64 s[0:1], vcc
	s_cbranch_execz .LBB0_625
	s_load_dwordx2 s[4:5], s[84:85], 0x90
	s_lshl_b32 s3, s98, 6
	v_mov_b32_e32 v0, s3
	v_mov_b32_e32 v2, 1
	s_waitcnt lgkmcnt(0)
	s_add_u32 s4, s4, 0x1400
	s_addc_u32 s5, s5, 0
	global_atomic_add v1, v0, v2, s[4:5] offset:128 sc0
	s_mul_i32 s6, s99, 5
	s_add_i32 s3, s6, -1
	s_lshl_b32 s6, s98, 6
	s_sub_u32 s6, s4, s6
	s_subb_u32 s7, s5, 0
	s_mul_i32 s4, s100, 5
	s_waitcnt vmcnt(0)
	v_cmp_ne_u32_e32 vcc, s3, v1
	s_cbranch_vccnz .Lsm5_early
	global_atomic_add v0, v2, s[6:7] offset:2176
	s_branch .Lsm5_wtop

; __device__ __forceinline__ void fast_grid_barrier(unsigned* base, int seam, int tid) {
;     asm volatile("s_waitcnt vmcnt(0)" ::: "memory");
;     __syncthreads();
;     if (tid == 0) {
;         unsigned* cnt = base + seam * 128;
;         unsigned* flg = cnt + 64;
;         __builtin_amdgcn_fence(__ATOMIC_RELEASE, "agent");
;         asm volatile("s_waitcnt vmcnt(0)" ::: "memory");
;         const unsigned old = __hip_atomic_fetch_add(cnt, 1u, __ATOMIC_RELAXED, __HIP_MEMORY_SCOPE_AGENT);
;         if (old == gridDim.x - 1) __hip_atomic_store(flg, 1u, __ATOMIC_RELAXED, __HIP_MEMORY_SCOPE_AGENT);
;         else { unsigned sp = 0; while (__hip_atomic_load(flg, __ATOMIC_RELAXED, __HIP_MEMORY_SCOPE_AGENT) == 0u) { __builtin_amdgcn_s_sleep(2); if (++sp > (1u << 22)) break; } }
;         __builtin_amdgcn_fence(__ATOMIC_ACQUIRE, "agent");
;         asm volatile("s_waitcnt vmcnt(0)" ::: "memory");
;     }
;     __syncthreads();
; }
.LBB0_692:
	s_waitcnt vmcnt(0)
	v_cmp_eq_u32_e32 vcc, 0, v202
	s_waitcnt vmcnt(0) lgkmcnt(0)
	s_barrier
	s_and_saveexec_b64 s[0:1], vcc
	s_cbranch_execz .LBB0_707
	s_load_dwordx2 s[4:5], s[84:85], 0x90
	s_lshl_b32 s3, s98, 6
	v_mov_b32_e32 v0, s3
	v_mov_b32_e32 v2, 1
	s_waitcnt lgkmcnt(0)
	s_add_u32 s4, s4, 0x1400
	s_addc_u32 s5, s5, 0
	global_atomic_add v1, v0, v2, s[4:5] offset:128 sc0
	s_mul_i32 s6, s99, 6
	s_add_i32 s3, s6, -1
	s_lshl_b32 s6, s98, 6
	s_sub_u32 s6, s4, s6
	s_subb_u32 s7, s5, 0
	s_mul_i32 s4, s100, 6
	s_waitcnt vmcnt(0)
	v_cmp_ne_u32_e32 vcc, s3, v1
	s_cbranch_vccnz .Lsm6_early
	buffer_wbl2 sc1
	s_waitcnt vmcnt(0)
	global_atomic_add v0, v2, s[6:7] offset:2176
	s_branch .Lsm6_wtop

; __device__ __forceinline__ void fast_grid_barrier(unsigned* base, int seam, int tid) {
;     asm volatile("s_waitcnt vmcnt(0)" ::: "memory");
;     __syncthreads();
;     if (tid == 0) {
;         unsigned* cnt = base + seam * 128;
;         unsigned* flg = cnt + 64;
;         __builtin_amdgcn_fence(__ATOMIC_RELEASE, "agent");
;         asm volatile("s_waitcnt vmcnt(0)" ::: "memory");
;         const unsigned old = __hip_atomic_fetch_add(cnt, 1u, __ATOMIC_RELAXED, __HIP_MEMORY_SCOPE_AGENT);
;         if (old == gridDim.x - 1) __hip_atomic_store(flg, 1u, __ATOMIC_RELAXED, __HIP_MEMORY_SCOPE_AGENT);
;         else { unsigned sp = 0; while (__hip_atomic_load(flg, __ATOMIC_RELAXED, __HIP_MEMORY_SCOPE_AGENT) == 0u) { __builtin_amdgcn_s_sleep(2); if (++sp > (1u << 22)) break; } }
;         __builtin_amdgcn_fence(__ATOMIC_ACQUIRE, "agent");
;         asm volatile("s_waitcnt vmcnt(0)" ::: "memory");
;     }
;     __syncthreads();
; }
.LBB0_1069:
	s_waitcnt lgkmcnt(0)
	s_cmp_lt_i32 s47, 9
	s_cbranch_scc1 .LBB0_1086
	s_waitcnt vmcnt(0)
	s_barrier
	s_mov_b64 s[0:1], exec
	v_readlane_b32 s4, v249, 8
	v_readlane_b32 s5, v249, 9
	s_and_b64 s[4:5], s[0:1], s[4:5]
	s_mov_b64 exec, s[4:5]
	s_cbranch_execz .LBB0_1085
	s_load_dwordx2 s[4:5], s[84:85], 0x90
	s_lshl_b32 s3, s98, 6
	v_mov_b32_e32 v0, s3
	v_mov_b32_e32 v2, 1
	s_waitcnt lgkmcnt(0)
	s_add_u32 s4, s4, 0x1400
	s_addc_u32 s5, s5, 0
	global_atomic_add v1, v0, v2, s[4:5] offset:128 sc0
	s_mul_i32 s6, s99, 7
	s_add_i32 s3, s6, -1
	s_lshl_b32 s6, s98, 6
	s_sub_u32 s6, s4, s6
	s_subb_u32 s7, s5, 0
	s_mul_i32 s4, s100, 7
	s_waitcnt vmcnt(0)
	v_cmp_ne_u32_e32 vcc, s3, v1
	s_cbranch_vccnz .Lsm7_early
	buffer_wbl2 sc1
	s_waitcnt vmcnt(0)
	global_atomic_add v0, v2, s[6:7] offset:2176
	s_branch .Lsm7_wtop
.Lsm7_early:
	s_mul_i32 s3, s99, 6
	v_cmp_ne_u32_e32 vcc, s3, v1
	s_cbranch_vccnz .Lsm7_wtop
	buffer_wbl2 sc1
